# v23 + first local arriver of each XCD issues an early buffer_wbl2 in the grid barriers
# baseline (speedup 1.0000x reference)
.LBB0_113:
	s_or_b64 exec, exec, s[8:9]
	v_cvt_f32_u32_e32 v6, v4
	s_waitcnt vmcnt(0)
	v_readfirstlane_b32 s0, v5
	v_sub_u32_e32 v5, 0, v4
	v_rcp_iflag_f32_e32 v6, v6
	v_add_u32_e32 v7, s0, v3
	v_mul_f32_e32 v6, 0x4f7ffffe, v6
	v_cvt_u32_f32_e32 v6, v6
	v_mul_lo_u32 v3, v5, v6
	v_mul_hi_u32 v3, v6, v3
	v_add_u32_e32 v3, v6, v3
	v_mul_hi_u32 v3, v7, v3
	v_mul_lo_u32 v5, v3, v4
	v_sub_u32_e32 v5, v7, v5
	v_add_u32_e32 v6, 1, v3
	v_cmp_ge_u32_e32 vcc, v5, v4
	s_nop 1
	v_cndmask_b32_e32 v3, v3, v6, vcc
	v_sub_u32_e32 v6, v5, v4
	v_cndmask_b32_e32 v5, v5, v6, vcc
	v_add_u32_e32 v6, 1, v3
	v_cmp_ge_u32_e32 vcc, v5, v4
	v_add_u32_e32 v5, 1, v7
	s_nop 0
	v_cndmask_b32_e32 v3, v3, v6, vcc
	v_mul_lo_u32 v6, v4, v3
	v_add_u32_e32 v4, v6, v4
	v_cmp_ne_u32_e32 vcc, v5, v4
	s_and_saveexec_b64 s[0:1], vcc
	s_xor_b64 s[6:7], exec, s[0:1]
	s_cbranch_execz .LBB0_127
	s_waitcnt lgkmcnt(0)
	v_cmp_ne_u32_e32 vcc, v7, v6
	s_cbranch_vccnz .Lmy_noclean_0
	buffer_wbl2 sc1
.Lmy_noclean_0:
	v_readlane_b32 s10, v251, 38
	v_readlane_b32 s11, v251, 39
	v_mov_b32_e32 v2, 0
	s_nop 3
	s_add_u32 s10, s10, 0x3500
	s_addc_u32 s11, s11, 0
	global_load_dword v2, v2, s[10:11] sc1
	s_waitcnt vmcnt(0)
	v_cmp_eq_u32_e32 vcc, v2, v3
	s_and_saveexec_b64 s[8:9], vcc
	s_cbranch_execz .LBB0_126
	s_mov_b32 s0, 1
	s_mov_b64 s[12:13], 0
	v_mov_b32_e32 v2, 0
	s_branch .LBB0_117
